# LPF: the work-queue atomic for a workgroup's next unit is issued when its current diff/FoX/NSA unit leaves the last tile loop, so the unit epilogue covers the atomic's latency
# baseline (speedup 1.0000x reference)
.Lfp_atomic:
	v_cmp_eq_u32_e32 vcc, 1, v255
	s_cbranch_vccz .Lfp_doatomic
	s_waitcnt vmcnt(0)
	v_add_u32_e32 v0, 0x200, v254
	v_mov_b32_e32 v255, 0
	s_branch .Lfp_have

.Ld5f_exit:
	s_waitcnt vmcnt(0)
	v_cmp_eq_u32_e64 s[0:1], 0, v156
	s_nop 1
	s_and_saveexec_b64 s[0:1], s[0:1]
	global_atomic_add v254, v1, v160, s[44:45] sc0
	v_mov_b32_e32 v255, 1
	s_mov_b64 exec, s[0:1]
	s_branch .LBB0_690

.Ld4_exit:
	s_waitcnt vmcnt(0)
	v_cmp_eq_u32_e64 s[0:1], 0, v156
	s_nop 1
	s_and_saveexec_b64 s[0:1], s[0:1]
	global_atomic_add v254, v1, v160, s[44:45] sc0
	v_mov_b32_e32 v255, 1
	s_mov_b64 exec, s[0:1]
